# REL-FIRST: grid-barrier XCD leaders release their XCD's waiters before waiting for their own release acknowledge and invalidating (on SPLIT-ACQ-HOIST)
# speedup vs baseline: 1.0071x; 1.0038x over previous
.LBB0_91:
	s_or_b64 exec, exec, s[10:11]
	s_mov_b64 s[10:11], exec
	v_mbcnt_lo_u32_b32 v1, s10, 0
	v_mbcnt_hi_u32_b32 v1, s11, v1
	v_cmp_eq_u32_e32 vcc, 0, v1
	s_and_saveexec_b64 s[12:13], vcc
	s_cbranch_execz .LBB0_93
	s_bcnt1_i32_b64 s0, s[10:11]
	v_mov_b32_e32 v1, 0x2000
	v_mov_b32_e32 v2, s0
	global_atomic_add v1, v2, s[8:9] offset:1024
.LBB0_93:
	s_or_b64 exec, exec, s[12:13]
	buffer_inv sc1
	s_waitcnt vmcnt(0)
